# static priority raise, other half: s_setprio 1 for waves 0-3 inside the GEMM k-loops
# baseline (speedup 1.0000x reference)
; #define MFMA(a, b, c) __builtin_amdgcn_mfma_f32_32x32x16_bf16((a), (b), (c), 0, 0, 0)
;     ...
;     auto issue_at = [&](int mm0, int nn0, int kt, int buf) {
;       char* lb = L0 + buf * BUFB;
; #pragma unroll
;       for (int i = 0; i < 4; ++i) {
;         const int seg = wv * 4 + i, row = seg * 8 + gl_row;
;         const int c = (lane & 7) ^ ((row >> 1) & 7);
;         const u16* ap = (kt < g.split) ? g.a0 + (size_t)(mm0 + row) * g.ld0 + kt * g.ks0 : g.a1 + (size_t)(mm0 + row) * g.ld1 + (kt - g.split) * 64;
;         __builtin_amdgcn_global_load_lds((const unsigned*)(ap + c * 8), (__attribute__((address_space(3))) unsigned*)(lb + seg * 1024 + lane * 16), 16, 0, 0);
;       }
; #pragma unroll
;       for (int i = 0; i < BN / 64; ++i) {
;         const int seg = wv * (BN / 64) + i, row = seg * 8 + gl_row;
;         const int c = (lane & 7) ^ ((row >> 1) & 7);
;         __builtin_amdgcn_global_load_lds((const unsigned*)(g.W + (size_t)(nn0 + row) * g.K + kt * 64 + c * 8),
;                                          (__attribute__((address_space(3))) unsigned*)(lb + 256 * 128 + seg * 1024 + lane * 16), 16, 0, 0);
;       }
;     };
;     auto issue = [&](int kt, int buf) { issue_at(m0, n0, kt, buf); };
;     auto compute2 = [&](int buf) {
;       const char* lb = L0 + buf * BUFB;
; #pragma unroll
;       for (int ks = 0; ks < 4; ++ks) {
;         const int c = ks * 2 + hh;
;         bf16x8 wf[2], xf[MI];
; #pragma unroll
;         for (int j = 0; j < 2; ++j) { const int r = wn * 64 + j * 32 + l32; wf[j] = *(const bf16x8*)(lb + 256 * 128 + r * 128 + ((c ^ ((r >> 1) & 7)) << 4)); }
; #pragma unroll
;         for (int i = 0; i < MI; ++i) { const int r = wm * (MI * 32) + i * 32 + l32; xf[i] = *(const bf16x8*)(lb + r * 128 + ((c ^ ((r >> 1) & 7)) << 4)); }
; #pragma unroll
;         for (int i = 0; i < MI; ++i) {
;           acc[i][0] = MFMA(wf[0], xf[i], acc[i][0]);
;           acc[i][1] = MFMA(wf[1], xf[i], acc[i][1]);
;         }
;       }
.LBB0_798:
	v_writelane_b32 v255, s60, 0
	v_writelane_b32 v255, s61, 1
	v_writelane_b32 v255, s62, 2
	v_writelane_b32 v255, s63, 3
	v_writelane_b32 v255, s64, 4
	v_add_u32_e32 v0, v168, v169
	v_add_u32_e32 v178, v160, v169
	v_add_u32_e32 v199, v162, v169
	v_add_u32_e32 v254, v166, v169
	s_nop 0
	v_readfirstlane_b32 s60, v0
	v_readfirstlane_b32 s61, v178
	v_readfirstlane_b32 s62, v199
	v_readfirstlane_b32 s63, v254
	v_readfirstlane_b32 s98, v179
	s_nop 3
	s_lshr_b32 s98, s98, 6
	s_cmp_lt_u32 s98, 4
	s_cbranch_scc0 .Lgemm_prio_798
	s_setprio 1

; #define MFMA(a, b, c) __builtin_amdgcn_mfma_f32_32x32x16_bf16((a), (b), (c), 0, 0, 0)
;     ...
;     auto issue_at = [&](int mm0, int nn0, int kt, int buf) {
;       char* lb = L0 + buf * BUFB;
; #pragma unroll
;       for (int i = 0; i < 4; ++i) {
;         const int seg = wv * 4 + i, row = seg * 8 + gl_row;
;         const int c = (lane & 7) ^ ((row >> 1) & 7);
;         const u16* ap = (kt < g.split) ? g.a0 + (size_t)(mm0 + row) * g.ld0 + kt * g.ks0 : g.a1 + (size_t)(mm0 + row) * g.ld1 + (kt - g.split) * 64;
;         __builtin_amdgcn_global_load_lds((const unsigned*)(ap + c * 8), (__attribute__((address_space(3))) unsigned*)(lb + seg * 1024 + lane * 16), 16, 0, 0);
;       }
; #pragma unroll
;       for (int i = 0; i < BN / 64; ++i) {
;         const int seg = wv * (BN / 64) + i, row = seg * 8 + gl_row;
;         const int c = (lane & 7) ^ ((row >> 1) & 7);
;         __builtin_amdgcn_global_load_lds((const unsigned*)(g.W + (size_t)(nn0 + row) * g.K + kt * 64 + c * 8),
;                                          (__attribute__((address_space(3))) unsigned*)(lb + 256 * 128 + seg * 1024 + lane * 16), 16, 0, 0);
;       }
;     };
;     auto issue = [&](int kt, int buf) { issue_at(m0, n0, kt, buf); };
;     auto compute2 = [&](int buf) {
;       const char* lb = L0 + buf * BUFB;
; #pragma unroll
;       for (int ks = 0; ks < 4; ++ks) {
;         const int c = ks * 2 + hh;
;         bf16x8 wf[2], xf[MI];
; #pragma unroll
;         for (int j = 0; j < 2; ++j) { const int r = wn * 64 + j * 32 + l32; wf[j] = *(const bf16x8*)(lb + 256 * 128 + r * 128 + ((c ^ ((r >> 1) & 7)) << 4)); }
; #pragma unroll
;         for (int i = 0; i < MI; ++i) { const int r = wm * (MI * 32) + i * 32 + l32; xf[i] = *(const bf16x8*)(lb + r * 128 + ((c ^ ((r >> 1) & 7)) << 4)); }
; #pragma unroll
;         for (int i = 0; i < MI; ++i) {
;           acc[i][0] = MFMA(wf[0], xf[i], acc[i][0]);
;           acc[i][1] = MFMA(wf[1], xf[i], acc[i][1]);
;         }
;       }
.LBB0_1274:
	v_writelane_b32 v255, s62, 0
	v_writelane_b32 v255, s63, 1
	v_writelane_b32 v255, s64, 2
	v_writelane_b32 v255, s65, 3
	v_writelane_b32 v255, s66, 4
	v_add_u32_e32 v228, v177, v178
	v_add_u32_e32 v229, v169, v178
	v_add_u32_e32 v230, v170, v178
	v_add_u32_e32 v231, v172, v178
	s_nop 0
	v_readfirstlane_b32 s62, v228
	v_readfirstlane_b32 s63, v229
	v_readfirstlane_b32 s64, v230
	v_readfirstlane_b32 s65, v231
	v_readfirstlane_b32 s98, v179
	s_nop 3
	s_lshr_b32 s98, s98, 6
	s_cmp_lt_u32 s98, 4
	s_cbranch_scc0 .Lgemm_prio_1274
	s_setprio 1

; #define MFMA(a, b, c) __builtin_amdgcn_mfma_f32_32x32x16_bf16((a), (b), (c), 0, 0, 0)
;     ...
;     auto issue_at = [&](int mm0, int nn0, int kt, int buf) {
;       char* lb = L0 + buf * BUFB;
; #pragma unroll
;       for (int i = 0; i < 4; ++i) {
;         const int seg = wv * 4 + i, row = seg * 8 + gl_row;
;         const int c = (lane & 7) ^ ((row >> 1) & 7);
;         const u16* ap = (kt < g.split) ? g.a0 + (size_t)(mm0 + row) * g.ld0 + kt * g.ks0 : g.a1 + (size_t)(mm0 + row) * g.ld1 + (kt - g.split) * 64;
;         __builtin_amdgcn_global_load_lds((const unsigned*)(ap + c * 8), (__attribute__((address_space(3))) unsigned*)(lb + seg * 1024 + lane * 16), 16, 0, 0);
;       }
; #pragma unroll
;       for (int i = 0; i < BN / 64; ++i) {
;         const int seg = wv * (BN / 64) + i, row = seg * 8 + gl_row;
;         const int c = (lane & 7) ^ ((row >> 1) & 7);
;         __builtin_amdgcn_global_load_lds((const unsigned*)(g.W + (size_t)(nn0 + row) * g.K + kt * 64 + c * 8),
;                                          (__attribute__((address_space(3))) unsigned*)(lb + 256 * 128 + seg * 1024 + lane * 16), 16, 0, 0);
;       }
;     };
;     auto issue = [&](int kt, int buf) { issue_at(m0, n0, kt, buf); };
;     auto compute2 = [&](int buf) {
;       const char* lb = L0 + buf * BUFB;
; #pragma unroll
;       for (int ks = 0; ks < 4; ++ks) {
;         const int c = ks * 2 + hh;
;         bf16x8 wf[2], xf[MI];
; #pragma unroll
;         for (int j = 0; j < 2; ++j) { const int r = wn * 64 + j * 32 + l32; wf[j] = *(const bf16x8*)(lb + 256 * 128 + r * 128 + ((c ^ ((r >> 1) & 7)) << 4)); }
; #pragma unroll
;         for (int i = 0; i < MI; ++i) { const int r = wm * (MI * 32) + i * 32 + l32; xf[i] = *(const bf16x8*)(lb + r * 128 + ((c ^ ((r >> 1) & 7)) << 4)); }
; #pragma unroll
;         for (int i = 0; i < MI; ++i) {
;           acc[i][0] = MFMA(wf[0], xf[i], acc[i][0]);
;           acc[i][1] = MFMA(wf[1], xf[i], acc[i][1]);
;         }
;       }
.LBB0_1371:
	s_waitcnt vmcnt(16)
	s_barrier
	v_writelane_b32 v255, s60, 0
	v_writelane_b32 v255, s61, 1
	v_writelane_b32 v255, s62, 2
	v_writelane_b32 v255, s63, 3
	v_writelane_b32 v255, s64, 4
	v_add_u32_e32 v0, v167, v168
	v_add_u32_e32 v175, v157, v168
	v_add_u32_e32 v178, v159, v168
	v_add_u32_e32 v199, v165, v168
	s_nop 0
	v_readfirstlane_b32 s60, v0
	v_readfirstlane_b32 s61, v175
	v_readfirstlane_b32 s62, v178
	v_readfirstlane_b32 s63, v199
	v_readfirstlane_b32 s98, v179
	s_nop 3
	s_lshr_b32 s98, s98, 6
	s_cmp_lt_u32 s98, 4
	s_cbranch_scc0 .Lgemm_prio_1371
	s_setprio 1
